# speedup vs baseline: 1.0186x; 1.0018x over previous
.LBB0_1405:
	s_ashr_i32 s21, s20, 31
	s_lshl_b64 s[20:21], s[20:21], 19
	s_add_u32 s2, s28, s20
	s_addc_u32 s25, s29, s21
	s_lshl_b32 s40, s39, 8
	s_ashr_i32 s41, s40, 31
	s_lshl_b64 s[22:23], s[40:41], 1
	s_add_u32 s24, s2, s22
	s_addc_u32 s25, s25, s23
	s_add_u32 s2, s92, s20
	s_addc_u32 s20, s93, s21
	s_add_u32 s22, s2, s22
	s_addc_u32 s23, s20, s23
	v_readlane_b32 s20, v255, 15
	v_readlane_b32 s21, v255, 16
	s_load_dwordx2 s[20:21], s[20:21], 0x90
	v_lshlrev_b32_e32 v132, 2, v188
	v_lshl_add_u64 v[130:131], s[24:25], 0, v[196:197]
	v_lshlrev_b32_e32 v0, 1, v188
	v_lshl_add_u64 v[130:131], v[130:131], 0, v[0:1]
	s_waitcnt lgkmcnt(0)
	s_add_u32 s2, s20, s34
	s_addc_u32 s39, s21, 0
	s_lshl_b64 s[20:21], s[40:41], 2
	s_add_u32 s20, s2, s20
	s_addc_u32 s21, s39, s21
	v_and_b32_e32 v176, 63, v182
	v_and_b32_e32 v174, 0x300, v132
	v_lshl_add_u32 v174, v176, 2, v174
	global_load_dword v175, v174, s[20:21]
	v_lshrrev_b32_e32 v173, 6, v182
	v_lshlrev_b32_e32 v173, 9, v173
	v_add_u32_e32 v173, 0x10000, v173
	v_and_b32_e32 v172, 48, v132
	v_add_u32_e32 v172, v173, v172
	v_lshl_add_u32 v173, v176, 2, v173
	v_mov_b64_e32 v[170:171], v[130:131]
	global_load_dwordx2 v[142:143], v[170:171], off
	global_load_dwordx2 v[144:145], v[170:171], off offset:32
	global_load_dwordx2 v[146:147], v[170:171], off offset:64
	global_load_dwordx2 v[148:149], v[170:171], off offset:96
	v_add_co_u32_e32 v170, vcc, 0x8000, v170
	s_nop 1
	v_addc_co_u32_e32 v171, vcc, 0, v171, vcc
	global_load_dwordx2 v[150:151], v[170:171], off
	global_load_dwordx2 v[152:153], v[170:171], off offset:32
	global_load_dwordx2 v[154:155], v[170:171], off offset:64
	global_load_dwordx2 v[156:157], v[170:171], off offset:96
	v_add_co_u32_e32 v170, vcc, 0x8000, v170
	s_nop 1
	v_addc_co_u32_e32 v171, vcc, 0, v171, vcc
	global_load_dwordx2 v[158:159], v[170:171], off
	global_load_dwordx2 v[160:161], v[170:171], off offset:32
	global_load_dwordx2 v[162:163], v[170:171], off offset:64
	global_load_dwordx2 v[164:165], v[170:171], off offset:96
	v_add_co_u32_e32 v170, vcc, 0x8000, v170
	s_nop 1
	v_addc_co_u32_e32 v171, vcc, 0, v171, vcc
	global_load_dwordx2 v[166:167], v[170:171], off
	global_load_dwordx2 v[168:169], v[170:171], off offset:32
	s_waitcnt vmcnt(14)
	ds_write_b32 v173, v175
	s_waitcnt lgkmcnt(0)
	ds_read_b128 v[134:137], v172
	s_waitcnt vmcnt(13)
	v_mov_b64_e32 v[138:139], v[142:143]
	global_load_dwordx2 v[142:143], v[170:171], off offset:64
	s_waitcnt lgkmcnt(0)
	v_add_f32_e32 v126, v126, v134
	v_add_f32_e32 v127, v127, v135
	v_mul_f32_e32 v126, 0xbfb8aa3b, v126
	v_mul_f32_e32 v127, 0xbfb8aa3b, v127
	v_exp_f32_e32 v126, v126
	v_exp_f32_e32 v127, v127
	v_lshlrev_b32_e32 v133, 16, v138
	v_and_b32_e32 v138, 0xffff0000, v138
	v_add_f32_e32 v126, 1.0, v126
	v_add_f32_e32 v127, 1.0, v127
	v_rcp_f32_e32 v126, v126
	v_rcp_f32_e32 v127, v127
	v_lshlrev_b32_e32 v140, 16, v139
	v_and_b32_e32 v139, 0xffff0000, v139
	v_mul_f32_e32 v126, v126, v133
	v_mul_f32_e32 v127, v127, v138
	v_cvt_pk_bf16_f32 v134, v126, v127
	v_add_f32_e32 v126, v128, v136
	v_add_f32_e32 v127, v129, v137
	v_mul_f32_e32 v126, 0xbfb8aa3b, v126
	v_mul_f32_e32 v127, 0xbfb8aa3b, v127
	v_exp_f32_e32 v126, v126
	v_exp_f32_e32 v127, v127
	v_add_f32_e32 v126, 1.0, v126
	v_add_f32_e32 v127, 1.0, v127
	v_rcp_f32_e32 v126, v126
	v_rcp_f32_e32 v127, v127
	v_mul_f32_e32 v126, v126, v140
	v_mul_f32_e32 v127, v127, v139
	v_cvt_pk_bf16_f32 v135, v126, v127
	v_lshl_add_u64 v[126:127], s[22:23], 0, v[196:197]
	v_lshl_add_u64 v[126:127], v[126:127], 0, v[0:1]
	global_store_dwordx2 v[126:127], v[134:135], off
	s_waitcnt vmcnt(14)
	v_mov_b64_e32 v[128:129], v[144:145]
	global_load_dwordx2 v[144:145], v[170:171], off offset:96
	v_add_co_u32_e32 v170, vcc, 0x8000, v170
	s_nop 1
	v_addc_co_u32_e32 v171, vcc, 0, v171, vcc
	ds_read_b128 v[134:137], v172 offset:64
	v_lshlrev_b32_e32 v133, 16, v128
	s_waitcnt lgkmcnt(0)
	v_add_f32_e32 v122, v122, v134
	v_add_f32_e32 v123, v123, v135
	v_mul_f32_e32 v122, 0xbfb8aa3b, v122
	v_mul_f32_e32 v123, 0xbfb8aa3b, v123
	v_exp_f32_e32 v122, v122
	v_exp_f32_e32 v123, v123
	v_and_b32_e32 v128, 0xffff0000, v128
	v_lshlrev_b32_e32 v138, 16, v129
	v_add_f32_e32 v122, 1.0, v122
	v_add_f32_e32 v123, 1.0, v123
	v_rcp_f32_e32 v122, v122
	v_rcp_f32_e32 v123, v123
	v_and_b32_e32 v129, 0xffff0000, v129
	v_mul_f32_e32 v122, v122, v133
	v_mul_f32_e32 v123, v123, v128
	v_cvt_pk_bf16_f32 v122, v122, v123
	v_add_f32_e32 v123, v124, v136
	v_mul_f32_e32 v123, 0xbfb8aa3b, v123
	v_add_f32_e32 v124, v125, v137
	v_exp_f32_e32 v123, v123
	v_mul_f32_e32 v124, 0xbfb8aa3b, v124
	v_exp_f32_e32 v124, v124
	v_add_f32_e32 v123, 1.0, v123
	v_rcp_f32_e32 v123, v123
	v_add_f32_e32 v124, 1.0, v124
	v_rcp_f32_e32 v124, v124
	v_mul_f32_e32 v123, v123, v138
	v_mul_f32_e32 v124, v124, v129
	v_cvt_pk_bf16_f32 v123, v123, v124
	global_store_dwordx2 v[126:127], v[122:123], off offset:32
	s_waitcnt vmcnt(15)
	v_mov_b64_e32 v[128:129], v[146:147]
	global_load_dwordx2 v[146:147], v[170:171], off
	ds_read_b128 v[122:125], v172 offset:128
	v_lshlrev_b32_e32 v133, 16, v128
	s_waitcnt lgkmcnt(0)
	v_add_f32_e32 v118, v118, v122
	v_add_f32_e32 v119, v119, v123
	v_mul_f32_e32 v118, 0xbfb8aa3b, v118
	v_mul_f32_e32 v119, 0xbfb8aa3b, v119
	v_exp_f32_e32 v118, v118
	v_exp_f32_e32 v119, v119
	v_and_b32_e32 v128, 0xffff0000, v128
	v_lshlrev_b32_e32 v134, 16, v129
	v_add_f32_e32 v118, 1.0, v118
	v_add_f32_e32 v119, 1.0, v119
	v_rcp_f32_e32 v118, v118
	v_rcp_f32_e32 v119, v119
	v_and_b32_e32 v129, 0xffff0000, v129
	v_mul_f32_e32 v118, v118, v133
	v_mul_f32_e32 v119, v119, v128
	v_cvt_pk_bf16_f32 v118, v118, v119
	v_add_f32_e32 v119, v120, v124
	v_mul_f32_e32 v119, 0xbfb8aa3b, v119
	v_add_f32_e32 v120, v121, v125
	v_exp_f32_e32 v119, v119
	v_mul_f32_e32 v120, 0xbfb8aa3b, v120
	v_exp_f32_e32 v120, v120
	v_add_f32_e32 v119, 1.0, v119
	v_rcp_f32_e32 v119, v119
	v_add_f32_e32 v120, 1.0, v120
	v_rcp_f32_e32 v120, v120
	v_mul_f32_e32 v119, v119, v134
	v_mul_f32_e32 v120, v120, v129
	v_cvt_pk_bf16_f32 v119, v119, v120
	global_store_dwordx2 v[126:127], v[118:119], off offset:64
	s_waitcnt vmcnt(16)
	v_mov_b64_e32 v[118:119], v[148:149]
	global_load_dwordx2 v[148:149], v[170:171], off offset:32
	ds_read_b128 v[120:123], v172 offset:192
	v_lshlrev_b32_e32 v124, 16, v118
	s_waitcnt lgkmcnt(0)
	v_add_f32_e32 v114, v114, v120
	v_add_f32_e32 v115, v115, v121
	v_mul_f32_e32 v114, 0xbfb8aa3b, v114
	v_mul_f32_e32 v115, 0xbfb8aa3b, v115
	v_exp_f32_e32 v114, v114
	v_exp_f32_e32 v115, v115
	v_and_b32_e32 v118, 0xffff0000, v118
	v_lshlrev_b32_e32 v125, 16, v119
	v_add_f32_e32 v114, 1.0, v114
	v_add_f32_e32 v115, 1.0, v115
	v_rcp_f32_e32 v114, v114
	v_rcp_f32_e32 v115, v115
	v_and_b32_e32 v119, 0xffff0000, v119
	v_mul_f32_e32 v114, v114, v124
	v_mul_f32_e32 v115, v115, v118
	v_cvt_pk_bf16_f32 v114, v114, v115
	v_add_f32_e32 v115, v116, v122
	v_mul_f32_e32 v115, 0xbfb8aa3b, v115
	v_add_f32_e32 v116, v117, v123
	v_exp_f32_e32 v115, v115
	v_mul_f32_e32 v116, 0xbfb8aa3b, v116
	v_exp_f32_e32 v116, v116
	v_add_f32_e32 v115, 1.0, v115
	v_rcp_f32_e32 v115, v115
	v_add_f32_e32 v116, 1.0, v116
	v_rcp_f32_e32 v116, v116
	v_mul_f32_e32 v115, v115, v125
	v_mul_f32_e32 v116, v116, v119
	v_cvt_pk_bf16_f32 v115, v115, v116
	global_store_dwordx2 v[126:127], v[114:115], off offset:96
	v_lshl_add_u64 v[114:115], s[24:25], 0, v[198:199]
	v_lshl_add_u64 v[114:115], v[114:115], 0, v[0:1]
	s_waitcnt vmcnt(17)
	v_mov_b64_e32 v[120:121], v[150:151]
	global_load_dwordx2 v[150:151], v[170:171], off offset:64
	ds_read_b128 v[116:119], v172
	v_lshlrev_b32_e32 v122, 16, v120
	s_waitcnt lgkmcnt(0)
	v_add_f32_e32 v110, v110, v116
	v_add_f32_e32 v111, v111, v117
	v_mul_f32_e32 v110, 0xbfb8aa3b, v110
	v_mul_f32_e32 v111, 0xbfb8aa3b, v111
	v_exp_f32_e32 v110, v110
	v_exp_f32_e32 v111, v111
	v_and_b32_e32 v120, 0xffff0000, v120
	v_lshlrev_b32_e32 v123, 16, v121
	v_add_f32_e32 v110, 1.0, v110
	v_add_f32_e32 v111, 1.0, v111
	v_rcp_f32_e32 v110, v110
	v_rcp_f32_e32 v111, v111
	v_and_b32_e32 v121, 0xffff0000, v121
	v_mul_f32_e32 v110, v110, v122
	v_mul_f32_e32 v111, v111, v120
	v_cvt_pk_bf16_f32 v116, v110, v111
	v_add_f32_e32 v110, v112, v118
	v_add_f32_e32 v111, v113, v119
	v_mul_f32_e32 v110, 0xbfb8aa3b, v110
	v_mul_f32_e32 v111, 0xbfb8aa3b, v111
	v_exp_f32_e32 v110, v110
	v_exp_f32_e32 v111, v111
	v_add_f32_e32 v110, 1.0, v110
	v_add_f32_e32 v111, 1.0, v111
	v_rcp_f32_e32 v110, v110
	v_rcp_f32_e32 v111, v111
	v_mul_f32_e32 v110, v110, v123
	v_mul_f32_e32 v111, v111, v121
	v_cvt_pk_bf16_f32 v117, v110, v111
	v_lshl_add_u64 v[110:111], s[22:23], 0, v[198:199]
	v_lshl_add_u64 v[110:111], v[110:111], 0, v[0:1]
	global_store_dwordx2 v[110:111], v[116:117], off
	s_waitcnt vmcnt(18)
	v_mov_b64_e32 v[112:113], v[152:153]
	global_load_dwordx2 v[152:153], v[170:171], off offset:96
	v_add_co_u32_e32 v170, vcc, 0x8000, v170
	s_nop 1
	v_addc_co_u32_e32 v171, vcc, 0, v171, vcc
	ds_read_b128 v[116:119], v172 offset:64
	v_lshlrev_b32_e32 v120, 16, v112
	s_waitcnt lgkmcnt(0)
	v_add_f32_e32 v106, v106, v116
	v_add_f32_e32 v107, v107, v117
	v_mul_f32_e32 v106, 0xbfb8aa3b, v106
	v_mul_f32_e32 v107, 0xbfb8aa3b, v107
	v_exp_f32_e32 v106, v106
	v_exp_f32_e32 v107, v107
	v_and_b32_e32 v112, 0xffff0000, v112
	v_lshlrev_b32_e32 v121, 16, v113
	v_add_f32_e32 v106, 1.0, v106
	v_add_f32_e32 v107, 1.0, v107
	v_rcp_f32_e32 v106, v106
	v_rcp_f32_e32 v107, v107
	v_and_b32_e32 v113, 0xffff0000, v113
	v_mul_f32_e32 v106, v106, v120
	v_mul_f32_e32 v107, v107, v112
	v_cvt_pk_bf16_f32 v106, v106, v107
	v_add_f32_e32 v107, v108, v118
	v_mul_f32_e32 v107, 0xbfb8aa3b, v107
	v_add_f32_e32 v108, v109, v119
	v_exp_f32_e32 v107, v107
	v_mul_f32_e32 v108, 0xbfb8aa3b, v108
	v_exp_f32_e32 v108, v108
	v_add_f32_e32 v107, 1.0, v107
	v_rcp_f32_e32 v107, v107
	v_add_f32_e32 v108, 1.0, v108
	v_rcp_f32_e32 v108, v108
	v_mul_f32_e32 v107, v107, v121
	v_mul_f32_e32 v108, v108, v113
	v_cvt_pk_bf16_f32 v107, v107, v108
	global_store_dwordx2 v[110:111], v[106:107], off offset:32
	s_waitcnt vmcnt(19)
	v_mov_b64_e32 v[112:113], v[154:155]
	global_load_dwordx2 v[154:155], v[170:171], off
	ds_read_b128 v[106:109], v172 offset:128
	v_lshlrev_b32_e32 v116, 16, v112
	s_waitcnt lgkmcnt(0)
	v_add_f32_e32 v102, v102, v106
	v_add_f32_e32 v103, v103, v107
	v_mul_f32_e32 v102, 0xbfb8aa3b, v102
	v_mul_f32_e32 v103, 0xbfb8aa3b, v103
	v_exp_f32_e32 v102, v102
	v_exp_f32_e32 v103, v103
	v_and_b32_e32 v112, 0xffff0000, v112
	v_lshlrev_b32_e32 v117, 16, v113
	v_add_f32_e32 v102, 1.0, v102
	v_add_f32_e32 v103, 1.0, v103
	v_rcp_f32_e32 v102, v102
	v_rcp_f32_e32 v103, v103
	v_and_b32_e32 v113, 0xffff0000, v113
	v_mul_f32_e32 v102, v102, v116
	v_mul_f32_e32 v103, v103, v112
	v_cvt_pk_bf16_f32 v102, v102, v103
	v_add_f32_e32 v103, v104, v108
	v_mul_f32_e32 v103, 0xbfb8aa3b, v103
	v_add_f32_e32 v104, v105, v109
	v_exp_f32_e32 v103, v103
	v_mul_f32_e32 v104, 0xbfb8aa3b, v104
	v_exp_f32_e32 v104, v104
	v_add_f32_e32 v103, 1.0, v103
	v_rcp_f32_e32 v103, v103
	v_add_f32_e32 v104, 1.0, v104
	v_rcp_f32_e32 v104, v104
	v_mul_f32_e32 v103, v103, v117
	v_mul_f32_e32 v104, v104, v113
	v_cvt_pk_bf16_f32 v103, v103, v104
	global_store_dwordx2 v[110:111], v[102:103], off offset:64
	s_waitcnt vmcnt(20)
	v_mov_b64_e32 v[102:103], v[156:157]
	global_load_dwordx2 v[156:157], v[170:171], off offset:32
	ds_read_b128 v[104:107], v172 offset:192
	v_lshlrev_b32_e32 v108, 16, v102
	s_waitcnt lgkmcnt(0)
	v_add_f32_e32 v98, v98, v104
	v_add_f32_e32 v99, v99, v105
	v_mul_f32_e32 v98, 0xbfb8aa3b, v98
	v_mul_f32_e32 v99, 0xbfb8aa3b, v99
	v_exp_f32_e32 v98, v98
	v_exp_f32_e32 v99, v99
	v_and_b32_e32 v102, 0xffff0000, v102
	v_lshlrev_b32_e32 v109, 16, v103
	v_add_f32_e32 v98, 1.0, v98
	v_add_f32_e32 v99, 1.0, v99
	v_rcp_f32_e32 v98, v98
	v_rcp_f32_e32 v99, v99
	v_and_b32_e32 v103, 0xffff0000, v103
	v_mul_f32_e32 v98, v98, v108
	v_mul_f32_e32 v99, v99, v102
	v_cvt_pk_bf16_f32 v98, v98, v99
	v_add_f32_e32 v99, v100, v106
	v_mul_f32_e32 v99, 0xbfb8aa3b, v99
	v_add_f32_e32 v100, v101, v107
	v_exp_f32_e32 v99, v99
	v_mul_f32_e32 v100, 0xbfb8aa3b, v100
	v_exp_f32_e32 v100, v100
	v_add_f32_e32 v99, 1.0, v99
	v_rcp_f32_e32 v99, v99
	v_add_f32_e32 v100, 1.0, v100
	v_rcp_f32_e32 v100, v100
	v_mul_f32_e32 v99, v99, v109
	v_mul_f32_e32 v100, v100, v103
	v_cvt_pk_bf16_f32 v99, v99, v100
	global_store_dwordx2 v[110:111], v[98:99], off offset:96
	v_lshl_add_u64 v[98:99], s[24:25], 0, v[200:201]
	v_lshl_add_u64 v[98:99], v[98:99], 0, v[0:1]
	s_waitcnt vmcnt(21)
	v_mov_b64_e32 v[104:105], v[158:159]
	global_load_dwordx2 v[158:159], v[170:171], off offset:64
	ds_read_b128 v[100:103], v172
	v_lshlrev_b32_e32 v106, 16, v104
	s_waitcnt lgkmcnt(0)
	v_add_f32_e32 v94, v94, v100
	v_add_f32_e32 v95, v95, v101
	v_mul_f32_e32 v94, 0xbfb8aa3b, v94
	v_mul_f32_e32 v95, 0xbfb8aa3b, v95
	v_exp_f32_e32 v94, v94
	v_exp_f32_e32 v95, v95
	v_and_b32_e32 v104, 0xffff0000, v104
	v_lshlrev_b32_e32 v107, 16, v105
	v_add_f32_e32 v94, 1.0, v94
	v_add_f32_e32 v95, 1.0, v95
	v_rcp_f32_e32 v94, v94
	v_rcp_f32_e32 v95, v95
	v_and_b32_e32 v105, 0xffff0000, v105
	v_mul_f32_e32 v94, v94, v106
	v_mul_f32_e32 v95, v95, v104
	v_cvt_pk_bf16_f32 v100, v94, v95
	v_add_f32_e32 v94, v96, v102
	v_add_f32_e32 v95, v97, v103
	v_mul_f32_e32 v94, 0xbfb8aa3b, v94
	v_mul_f32_e32 v95, 0xbfb8aa3b, v95
	v_exp_f32_e32 v94, v94
	v_exp_f32_e32 v95, v95
	v_add_f32_e32 v94, 1.0, v94
	v_add_f32_e32 v95, 1.0, v95
	v_rcp_f32_e32 v94, v94
	v_rcp_f32_e32 v95, v95
	v_mul_f32_e32 v94, v94, v107
	v_mul_f32_e32 v95, v95, v105
	v_cvt_pk_bf16_f32 v101, v94, v95
	v_lshl_add_u64 v[94:95], s[22:23], 0, v[200:201]
	v_lshl_add_u64 v[94:95], v[94:95], 0, v[0:1]
	global_store_dwordx2 v[94:95], v[100:101], off
	s_waitcnt vmcnt(22)
	v_mov_b64_e32 v[96:97], v[160:161]
	global_load_dwordx2 v[160:161], v[170:171], off offset:96
	v_add_co_u32_e32 v170, vcc, 0x8000, v170
	s_nop 1
	v_addc_co_u32_e32 v171, vcc, 0, v171, vcc
	ds_read_b128 v[100:103], v172 offset:64
	v_lshlrev_b32_e32 v104, 16, v96
	s_waitcnt lgkmcnt(0)
	v_add_f32_e32 v90, v90, v100
	v_add_f32_e32 v91, v91, v101
	v_mul_f32_e32 v90, 0xbfb8aa3b, v90
	v_mul_f32_e32 v91, 0xbfb8aa3b, v91
	v_exp_f32_e32 v90, v90
	v_exp_f32_e32 v91, v91
	v_and_b32_e32 v96, 0xffff0000, v96
	v_lshlrev_b32_e32 v105, 16, v97
	v_add_f32_e32 v90, 1.0, v90
	v_add_f32_e32 v91, 1.0, v91
	v_rcp_f32_e32 v90, v90
	v_rcp_f32_e32 v91, v91
	v_and_b32_e32 v97, 0xffff0000, v97
	v_mul_f32_e32 v90, v90, v104
	v_mul_f32_e32 v91, v91, v96
	v_cvt_pk_bf16_f32 v90, v90, v91
	v_add_f32_e32 v91, v92, v102
	v_mul_f32_e32 v91, 0xbfb8aa3b, v91
	v_add_f32_e32 v92, v93, v103
	v_exp_f32_e32 v91, v91
	v_mul_f32_e32 v92, 0xbfb8aa3b, v92
	v_exp_f32_e32 v92, v92
	v_add_f32_e32 v91, 1.0, v91
	v_rcp_f32_e32 v91, v91
	v_add_f32_e32 v92, 1.0, v92
	v_rcp_f32_e32 v92, v92
	v_mul_f32_e32 v91, v91, v105
	v_mul_f32_e32 v92, v92, v97
	v_cvt_pk_bf16_f32 v91, v91, v92
	global_store_dwordx2 v[94:95], v[90:91], off offset:32
	s_waitcnt vmcnt(23)
	v_mov_b64_e32 v[96:97], v[162:163]
	global_load_dwordx2 v[162:163], v[170:171], off
	ds_read_b128 v[90:93], v172 offset:128
	v_lshlrev_b32_e32 v100, 16, v96
	s_waitcnt lgkmcnt(0)
	v_add_f32_e32 v86, v86, v90
	v_add_f32_e32 v87, v87, v91
	v_mul_f32_e32 v86, 0xbfb8aa3b, v86
	v_mul_f32_e32 v87, 0xbfb8aa3b, v87
	v_exp_f32_e32 v86, v86
	v_exp_f32_e32 v87, v87
	v_and_b32_e32 v96, 0xffff0000, v96
	v_lshlrev_b32_e32 v101, 16, v97
	v_add_f32_e32 v86, 1.0, v86
	v_add_f32_e32 v87, 1.0, v87
	v_rcp_f32_e32 v86, v86
	v_rcp_f32_e32 v87, v87
	v_and_b32_e32 v97, 0xffff0000, v97
	v_mul_f32_e32 v86, v86, v100
	v_mul_f32_e32 v87, v87, v96
	v_cvt_pk_bf16_f32 v86, v86, v87
	v_add_f32_e32 v87, v88, v92
	v_mul_f32_e32 v87, 0xbfb8aa3b, v87
	v_add_f32_e32 v88, v89, v93
	v_exp_f32_e32 v87, v87
	v_mul_f32_e32 v88, 0xbfb8aa3b, v88
	v_exp_f32_e32 v88, v88
	v_add_f32_e32 v87, 1.0, v87
	v_rcp_f32_e32 v87, v87
	v_add_f32_e32 v88, 1.0, v88
	v_rcp_f32_e32 v88, v88
	v_mul_f32_e32 v87, v87, v101
	v_mul_f32_e32 v88, v88, v97
	v_cvt_pk_bf16_f32 v87, v87, v88
	global_store_dwordx2 v[94:95], v[86:87], off offset:64
	s_waitcnt vmcnt(24)
	v_mov_b64_e32 v[86:87], v[164:165]
	global_load_dwordx2 v[164:165], v[170:171], off offset:32
	ds_read_b128 v[88:91], v172 offset:192
	v_lshlrev_b32_e32 v92, 16, v86
	s_waitcnt lgkmcnt(0)
	v_add_f32_e32 v82, v82, v88
	v_add_f32_e32 v83, v83, v89
	v_mul_f32_e32 v82, 0xbfb8aa3b, v82
	v_mul_f32_e32 v83, 0xbfb8aa3b, v83
	v_exp_f32_e32 v82, v82
	v_exp_f32_e32 v83, v83
	v_and_b32_e32 v86, 0xffff0000, v86
	v_lshlrev_b32_e32 v93, 16, v87
	v_add_f32_e32 v82, 1.0, v82
	v_add_f32_e32 v83, 1.0, v83
	v_rcp_f32_e32 v82, v82
	v_rcp_f32_e32 v83, v83
	v_and_b32_e32 v87, 0xffff0000, v87
	v_mul_f32_e32 v82, v82, v92
	v_mul_f32_e32 v83, v83, v86
	v_cvt_pk_bf16_f32 v82, v82, v83
	v_add_f32_e32 v83, v84, v90
	v_mul_f32_e32 v83, 0xbfb8aa3b, v83
	v_add_f32_e32 v84, v85, v91
	v_exp_f32_e32 v83, v83
	v_mul_f32_e32 v84, 0xbfb8aa3b, v84
	v_exp_f32_e32 v84, v84
	v_add_f32_e32 v83, 1.0, v83
	v_rcp_f32_e32 v83, v83
	v_add_f32_e32 v84, 1.0, v84
	v_rcp_f32_e32 v84, v84
	v_mul_f32_e32 v83, v83, v93
	v_mul_f32_e32 v84, v84, v87
	v_cvt_pk_bf16_f32 v83, v83, v84
	global_store_dwordx2 v[94:95], v[82:83], off offset:96
	v_lshl_add_u64 v[82:83], s[24:25], 0, v[202:203]
	v_lshl_add_u64 v[82:83], v[82:83], 0, v[0:1]
	s_waitcnt vmcnt(25)
	v_mov_b64_e32 v[88:89], v[166:167]
	global_load_dwordx2 v[166:167], v[170:171], off offset:64
	ds_read_b128 v[84:87], v172
	v_lshlrev_b32_e32 v90, 16, v88
	s_waitcnt lgkmcnt(0)
	v_add_f32_e32 v78, v78, v84
	v_add_f32_e32 v79, v79, v85
	v_mul_f32_e32 v78, 0xbfb8aa3b, v78
	v_mul_f32_e32 v79, 0xbfb8aa3b, v79
	v_exp_f32_e32 v78, v78
	v_exp_f32_e32 v79, v79
	v_and_b32_e32 v88, 0xffff0000, v88
	v_lshlrev_b32_e32 v91, 16, v89
	v_add_f32_e32 v78, 1.0, v78
	v_add_f32_e32 v79, 1.0, v79
	v_rcp_f32_e32 v78, v78
	v_rcp_f32_e32 v79, v79
	v_and_b32_e32 v89, 0xffff0000, v89
	v_mul_f32_e32 v78, v78, v90
	v_mul_f32_e32 v79, v79, v88
	v_cvt_pk_bf16_f32 v84, v78, v79
	v_add_f32_e32 v78, v80, v86
	v_add_f32_e32 v79, v81, v87
	v_mul_f32_e32 v78, 0xbfb8aa3b, v78
	v_mul_f32_e32 v79, 0xbfb8aa3b, v79
	v_exp_f32_e32 v78, v78
	v_exp_f32_e32 v79, v79
	v_add_f32_e32 v78, 1.0, v78
	v_add_f32_e32 v79, 1.0, v79
	v_rcp_f32_e32 v78, v78
	v_rcp_f32_e32 v79, v79
	v_mul_f32_e32 v78, v78, v91
	v_mul_f32_e32 v79, v79, v89
	v_cvt_pk_bf16_f32 v85, v78, v79
	v_lshl_add_u64 v[78:79], s[22:23], 0, v[202:203]
	v_lshl_add_u64 v[78:79], v[78:79], 0, v[0:1]
	global_store_dwordx2 v[78:79], v[84:85], off
	s_waitcnt vmcnt(26)
	v_mov_b64_e32 v[80:81], v[168:169]
	global_load_dwordx2 v[168:169], v[170:171], off offset:96
	v_add_co_u32_e32 v170, vcc, 0x8000, v170
	s_nop 1
	v_addc_co_u32_e32 v171, vcc, 0, v171, vcc
	ds_read_b128 v[84:87], v172 offset:64
	v_lshlrev_b32_e32 v88, 16, v80
	s_waitcnt lgkmcnt(0)
	v_add_f32_e32 v74, v74, v84
	v_add_f32_e32 v75, v75, v85
	v_mul_f32_e32 v74, 0xbfb8aa3b, v74
	v_mul_f32_e32 v75, 0xbfb8aa3b, v75
	v_exp_f32_e32 v74, v74
	v_exp_f32_e32 v75, v75
	v_and_b32_e32 v80, 0xffff0000, v80
	v_lshlrev_b32_e32 v89, 16, v81
	v_add_f32_e32 v74, 1.0, v74
	v_add_f32_e32 v75, 1.0, v75
	v_rcp_f32_e32 v74, v74
	v_rcp_f32_e32 v75, v75
	v_and_b32_e32 v81, 0xffff0000, v81
	v_mul_f32_e32 v74, v74, v88
	v_mul_f32_e32 v75, v75, v80
	v_cvt_pk_bf16_f32 v74, v74, v75
	v_add_f32_e32 v75, v76, v86
	v_mul_f32_e32 v75, 0xbfb8aa3b, v75
	v_add_f32_e32 v76, v77, v87
	v_exp_f32_e32 v75, v75
	v_mul_f32_e32 v76, 0xbfb8aa3b, v76
	v_exp_f32_e32 v76, v76
	v_add_f32_e32 v75, 1.0, v75
	v_rcp_f32_e32 v75, v75
	v_add_f32_e32 v76, 1.0, v76
	v_rcp_f32_e32 v76, v76
	v_mul_f32_e32 v75, v75, v89
	v_mul_f32_e32 v76, v76, v81
	v_cvt_pk_bf16_f32 v75, v75, v76
	global_store_dwordx2 v[78:79], v[74:75], off offset:32
	s_waitcnt vmcnt(27)
	v_mov_b64_e32 v[80:81], v[142:143]
	global_load_dwordx2 v[142:143], v[170:171], off
	ds_read_b128 v[74:77], v172 offset:128
	v_lshlrev_b32_e32 v84, 16, v80
	s_waitcnt lgkmcnt(0)
	v_add_f32_e32 v70, v70, v74
	v_add_f32_e32 v71, v71, v75
	v_mul_f32_e32 v70, 0xbfb8aa3b, v70
	v_mul_f32_e32 v71, 0xbfb8aa3b, v71
	v_exp_f32_e32 v70, v70
	v_exp_f32_e32 v71, v71
	v_and_b32_e32 v80, 0xffff0000, v80
	v_lshlrev_b32_e32 v85, 16, v81
	v_add_f32_e32 v70, 1.0, v70
	v_add_f32_e32 v71, 1.0, v71
	v_rcp_f32_e32 v70, v70
	v_rcp_f32_e32 v71, v71
	v_and_b32_e32 v81, 0xffff0000, v81
	v_mul_f32_e32 v70, v70, v84
	v_mul_f32_e32 v71, v71, v80
	v_cvt_pk_bf16_f32 v70, v70, v71
	v_add_f32_e32 v71, v72, v76
	v_mul_f32_e32 v71, 0xbfb8aa3b, v71
	v_add_f32_e32 v72, v73, v77
	v_exp_f32_e32 v71, v71
	v_mul_f32_e32 v72, 0xbfb8aa3b, v72
	v_exp_f32_e32 v72, v72
	v_add_f32_e32 v71, 1.0, v71
	v_rcp_f32_e32 v71, v71
	v_add_f32_e32 v72, 1.0, v72
	v_rcp_f32_e32 v72, v72
	v_mul_f32_e32 v71, v71, v85
	v_mul_f32_e32 v72, v72, v81
	v_cvt_pk_bf16_f32 v71, v71, v72
	global_store_dwordx2 v[78:79], v[70:71], off offset:64
	s_waitcnt vmcnt(27)
	v_mov_b64_e32 v[70:71], v[144:145]
	global_load_dwordx2 v[144:145], v[170:171], off offset:32
	ds_read_b128 v[72:75], v172 offset:192
	v_lshlrev_b32_e32 v76, 16, v70
	s_waitcnt lgkmcnt(0)
	v_add_f32_e32 v66, v66, v72
	v_add_f32_e32 v67, v67, v73
	v_mul_f32_e32 v66, 0xbfb8aa3b, v66
	v_mul_f32_e32 v67, 0xbfb8aa3b, v67
	v_exp_f32_e32 v66, v66
	v_exp_f32_e32 v67, v67
	v_and_b32_e32 v70, 0xffff0000, v70
	v_lshlrev_b32_e32 v77, 16, v71
	v_add_f32_e32 v66, 1.0, v66
	v_add_f32_e32 v67, 1.0, v67
	v_rcp_f32_e32 v66, v66
	v_rcp_f32_e32 v67, v67
	v_and_b32_e32 v71, 0xffff0000, v71
	v_mul_f32_e32 v66, v66, v76
	v_mul_f32_e32 v67, v67, v70
	v_cvt_pk_bf16_f32 v66, v66, v67
	v_add_f32_e32 v67, v68, v74
	v_mul_f32_e32 v67, 0xbfb8aa3b, v67
	v_add_f32_e32 v68, v69, v75
	v_exp_f32_e32 v67, v67
	v_mul_f32_e32 v68, 0xbfb8aa3b, v68
	v_exp_f32_e32 v68, v68
	v_add_f32_e32 v67, 1.0, v67
	v_rcp_f32_e32 v67, v67
	v_add_f32_e32 v68, 1.0, v68
	v_rcp_f32_e32 v68, v68
	v_mul_f32_e32 v67, v67, v77
	v_mul_f32_e32 v68, v68, v71
	v_cvt_pk_bf16_f32 v67, v67, v68
	global_store_dwordx2 v[78:79], v[66:67], off offset:96
	v_lshl_add_u64 v[66:67], s[24:25], 0, v[204:205]
	v_lshl_add_u64 v[66:67], v[66:67], 0, v[0:1]
	s_waitcnt vmcnt(27)
	v_mov_b64_e32 v[72:73], v[146:147]
	global_load_dwordx2 v[146:147], v[170:171], off offset:64
	ds_read_b128 v[68:71], v172
	v_lshlrev_b32_e32 v74, 16, v72
	s_waitcnt lgkmcnt(0)
	v_add_f32_e32 v62, v62, v68
	v_add_f32_e32 v63, v63, v69
	v_mul_f32_e32 v62, 0xbfb8aa3b, v62
	v_mul_f32_e32 v63, 0xbfb8aa3b, v63
	v_exp_f32_e32 v62, v62
	v_exp_f32_e32 v63, v63
	v_and_b32_e32 v72, 0xffff0000, v72
	v_lshlrev_b32_e32 v75, 16, v73
	v_add_f32_e32 v62, 1.0, v62
	v_add_f32_e32 v63, 1.0, v63
	v_rcp_f32_e32 v62, v62
	v_rcp_f32_e32 v63, v63
	v_and_b32_e32 v73, 0xffff0000, v73
	v_mul_f32_e32 v62, v62, v74
	v_mul_f32_e32 v63, v63, v72
	v_cvt_pk_bf16_f32 v68, v62, v63
	v_add_f32_e32 v62, v64, v70
	v_add_f32_e32 v63, v65, v71
	v_mul_f32_e32 v62, 0xbfb8aa3b, v62
	v_mul_f32_e32 v63, 0xbfb8aa3b, v63
	v_exp_f32_e32 v62, v62
	v_exp_f32_e32 v63, v63
	v_add_f32_e32 v62, 1.0, v62
	v_add_f32_e32 v63, 1.0, v63
	v_rcp_f32_e32 v62, v62
	v_rcp_f32_e32 v63, v63
	v_mul_f32_e32 v62, v62, v75
	v_mul_f32_e32 v63, v63, v73
	v_cvt_pk_bf16_f32 v69, v62, v63
	v_lshl_add_u64 v[62:63], s[22:23], 0, v[204:205]
	v_lshl_add_u64 v[62:63], v[62:63], 0, v[0:1]
	global_store_dwordx2 v[62:63], v[68:69], off
	s_waitcnt vmcnt(27)
	v_mov_b64_e32 v[64:65], v[148:149]
	global_load_dwordx2 v[148:149], v[170:171], off offset:96
	ds_read_b128 v[68:71], v172 offset:64
	v_lshlrev_b32_e32 v72, 16, v64
	s_waitcnt lgkmcnt(0)
	v_add_f32_e32 v58, v58, v68
	v_add_f32_e32 v59, v59, v69
	v_mul_f32_e32 v58, 0xbfb8aa3b, v58
	v_mul_f32_e32 v59, 0xbfb8aa3b, v59
	v_exp_f32_e32 v58, v58
	v_exp_f32_e32 v59, v59
	v_and_b32_e32 v64, 0xffff0000, v64
	v_lshlrev_b32_e32 v73, 16, v65
	v_add_f32_e32 v58, 1.0, v58
	v_add_f32_e32 v59, 1.0, v59
	v_rcp_f32_e32 v58, v58
	v_rcp_f32_e32 v59, v59
	v_and_b32_e32 v65, 0xffff0000, v65
	v_mul_f32_e32 v58, v58, v72
	v_mul_f32_e32 v59, v59, v64
	v_cvt_pk_bf16_f32 v58, v58, v59
	v_add_f32_e32 v59, v60, v70
	v_mul_f32_e32 v59, 0xbfb8aa3b, v59
	v_add_f32_e32 v60, v61, v71
	v_exp_f32_e32 v59, v59
	v_mul_f32_e32 v60, 0xbfb8aa3b, v60
	v_exp_f32_e32 v60, v60
	v_add_f32_e32 v59, 1.0, v59
	v_rcp_f32_e32 v59, v59
	v_add_f32_e32 v60, 1.0, v60
	v_rcp_f32_e32 v60, v60
	v_mul_f32_e32 v59, v59, v73
	v_mul_f32_e32 v60, v60, v65
	v_cvt_pk_bf16_f32 v59, v59, v60
	global_store_dwordx2 v[62:63], v[58:59], off offset:32
	s_waitcnt vmcnt(27)
	v_mov_b64_e32 v[64:65], v[150:151]
	ds_read_b128 v[58:61], v172 offset:128
	v_lshlrev_b32_e32 v68, 16, v64
	s_waitcnt lgkmcnt(0)
	v_add_f32_e32 v54, v54, v58
	v_add_f32_e32 v55, v55, v59
	v_mul_f32_e32 v54, 0xbfb8aa3b, v54
	v_mul_f32_e32 v55, 0xbfb8aa3b, v55
	v_exp_f32_e32 v54, v54
	v_exp_f32_e32 v55, v55
	v_and_b32_e32 v64, 0xffff0000, v64
	v_lshlrev_b32_e32 v69, 16, v65
	v_add_f32_e32 v54, 1.0, v54
	v_add_f32_e32 v55, 1.0, v55
	v_rcp_f32_e32 v54, v54
	v_rcp_f32_e32 v55, v55
	v_and_b32_e32 v65, 0xffff0000, v65
	v_mul_f32_e32 v54, v54, v68
	v_mul_f32_e32 v55, v55, v64
	v_cvt_pk_bf16_f32 v54, v54, v55
	v_add_f32_e32 v55, v56, v60
	v_mul_f32_e32 v55, 0xbfb8aa3b, v55
	v_add_f32_e32 v56, v57, v61
	v_exp_f32_e32 v55, v55
	v_mul_f32_e32 v56, 0xbfb8aa3b, v56
	v_exp_f32_e32 v56, v56
	v_add_f32_e32 v55, 1.0, v55
	v_rcp_f32_e32 v55, v55
	v_add_f32_e32 v56, 1.0, v56
	v_rcp_f32_e32 v56, v56
	v_mul_f32_e32 v55, v55, v69
	v_mul_f32_e32 v56, v56, v65
	v_cvt_pk_bf16_f32 v55, v55, v56
	global_store_dwordx2 v[62:63], v[54:55], off offset:64
	s_waitcnt vmcnt(26)
	v_mov_b64_e32 v[54:55], v[152:153]
	ds_read_b128 v[56:59], v172 offset:192
	v_lshlrev_b32_e32 v60, 16, v54
	s_waitcnt lgkmcnt(0)
	v_add_f32_e32 v50, v50, v56
	v_add_f32_e32 v51, v51, v57
	v_mul_f32_e32 v50, 0xbfb8aa3b, v50
	v_mul_f32_e32 v51, 0xbfb8aa3b, v51
	v_exp_f32_e32 v50, v50
	v_exp_f32_e32 v51, v51
	v_and_b32_e32 v54, 0xffff0000, v54
	v_lshlrev_b32_e32 v61, 16, v55
	v_add_f32_e32 v50, 1.0, v50
	v_add_f32_e32 v51, 1.0, v51
	v_rcp_f32_e32 v50, v50
	v_rcp_f32_e32 v51, v51
	v_and_b32_e32 v55, 0xffff0000, v55
	v_mul_f32_e32 v50, v50, v60
	v_mul_f32_e32 v51, v51, v54
	v_cvt_pk_bf16_f32 v50, v50, v51
	v_add_f32_e32 v51, v52, v58
	v_mul_f32_e32 v51, 0xbfb8aa3b, v51
	v_add_f32_e32 v52, v53, v59
	v_exp_f32_e32 v51, v51
	v_mul_f32_e32 v52, 0xbfb8aa3b, v52
	v_exp_f32_e32 v52, v52
	v_add_f32_e32 v51, 1.0, v51
	v_rcp_f32_e32 v51, v51
	v_add_f32_e32 v52, 1.0, v52
	v_rcp_f32_e32 v52, v52
	v_mul_f32_e32 v51, v51, v61
	v_mul_f32_e32 v52, v52, v55
	v_cvt_pk_bf16_f32 v51, v51, v52
	global_store_dwordx2 v[62:63], v[50:51], off offset:96
	v_lshl_add_u64 v[50:51], s[24:25], 0, v[206:207]
	v_lshl_add_u64 v[50:51], v[50:51], 0, v[0:1]
	s_waitcnt vmcnt(25)
	v_mov_b64_e32 v[56:57], v[154:155]
	ds_read_b128 v[52:55], v172
	v_lshlrev_b32_e32 v58, 16, v56
	s_waitcnt lgkmcnt(0)
	v_add_f32_e32 v46, v46, v52
	v_add_f32_e32 v47, v47, v53
	v_mul_f32_e32 v46, 0xbfb8aa3b, v46
	v_mul_f32_e32 v47, 0xbfb8aa3b, v47
	v_exp_f32_e32 v46, v46
	v_exp_f32_e32 v47, v47
	v_and_b32_e32 v56, 0xffff0000, v56
	v_lshlrev_b32_e32 v59, 16, v57
	v_add_f32_e32 v46, 1.0, v46
	v_add_f32_e32 v47, 1.0, v47
	v_rcp_f32_e32 v46, v46
	v_rcp_f32_e32 v47, v47
	v_and_b32_e32 v57, 0xffff0000, v57
	v_mul_f32_e32 v46, v46, v58
	v_mul_f32_e32 v47, v47, v56
	v_cvt_pk_bf16_f32 v52, v46, v47
	v_add_f32_e32 v46, v48, v54
	v_add_f32_e32 v47, v49, v55
	v_mul_f32_e32 v46, 0xbfb8aa3b, v46
	v_mul_f32_e32 v47, 0xbfb8aa3b, v47
	v_exp_f32_e32 v46, v46
	v_exp_f32_e32 v47, v47
	v_add_f32_e32 v46, 1.0, v46
	v_add_f32_e32 v47, 1.0, v47
	v_rcp_f32_e32 v46, v46
	v_rcp_f32_e32 v47, v47
	v_mul_f32_e32 v46, v46, v59
	v_mul_f32_e32 v47, v47, v57
	v_cvt_pk_bf16_f32 v53, v46, v47
	v_lshl_add_u64 v[46:47], s[22:23], 0, v[206:207]
	v_lshl_add_u64 v[46:47], v[46:47], 0, v[0:1]
	global_store_dwordx2 v[46:47], v[52:53], off
	s_waitcnt vmcnt(24)
	v_mov_b64_e32 v[48:49], v[156:157]
	ds_read_b128 v[52:55], v172 offset:64
	v_lshlrev_b32_e32 v56, 16, v48
	s_waitcnt lgkmcnt(0)
	v_add_f32_e32 v42, v42, v52
	v_add_f32_e32 v43, v43, v53
	v_mul_f32_e32 v42, 0xbfb8aa3b, v42
	v_mul_f32_e32 v43, 0xbfb8aa3b, v43
	v_exp_f32_e32 v42, v42
	v_exp_f32_e32 v43, v43
	v_and_b32_e32 v48, 0xffff0000, v48
	v_lshlrev_b32_e32 v57, 16, v49
	v_add_f32_e32 v42, 1.0, v42
	v_add_f32_e32 v43, 1.0, v43
	v_rcp_f32_e32 v42, v42
	v_rcp_f32_e32 v43, v43
	v_and_b32_e32 v49, 0xffff0000, v49
	v_mul_f32_e32 v42, v42, v56
	v_mul_f32_e32 v43, v43, v48
	v_cvt_pk_bf16_f32 v42, v42, v43
	v_add_f32_e32 v43, v44, v54
	v_mul_f32_e32 v43, 0xbfb8aa3b, v43
	v_add_f32_e32 v44, v45, v55
	v_exp_f32_e32 v43, v43
	v_mul_f32_e32 v44, 0xbfb8aa3b, v44
	v_exp_f32_e32 v44, v44
	v_add_f32_e32 v43, 1.0, v43
	v_rcp_f32_e32 v43, v43
	v_add_f32_e32 v44, 1.0, v44
	v_rcp_f32_e32 v44, v44
	v_mul_f32_e32 v43, v43, v57
	v_mul_f32_e32 v44, v44, v49
	v_cvt_pk_bf16_f32 v43, v43, v44
	global_store_dwordx2 v[46:47], v[42:43], off offset:32
	s_waitcnt vmcnt(23)
	v_mov_b64_e32 v[48:49], v[158:159]
	ds_read_b128 v[42:45], v172 offset:128
	v_lshlrev_b32_e32 v52, 16, v48
	s_waitcnt lgkmcnt(0)
	v_add_f32_e32 v38, v38, v42
	v_add_f32_e32 v39, v39, v43
	v_mul_f32_e32 v38, 0xbfb8aa3b, v38
	v_mul_f32_e32 v39, 0xbfb8aa3b, v39
	v_exp_f32_e32 v38, v38
	v_exp_f32_e32 v39, v39
	v_and_b32_e32 v48, 0xffff0000, v48
	v_lshlrev_b32_e32 v53, 16, v49
	v_add_f32_e32 v38, 1.0, v38
	v_add_f32_e32 v39, 1.0, v39
	v_rcp_f32_e32 v38, v38
	v_rcp_f32_e32 v39, v39
	v_and_b32_e32 v49, 0xffff0000, v49
	v_mul_f32_e32 v38, v38, v52
	v_mul_f32_e32 v39, v39, v48
	v_cvt_pk_bf16_f32 v38, v38, v39
	v_add_f32_e32 v39, v40, v44
	v_mul_f32_e32 v39, 0xbfb8aa3b, v39
	v_add_f32_e32 v40, v41, v45
	v_exp_f32_e32 v39, v39
	v_mul_f32_e32 v40, 0xbfb8aa3b, v40
	v_exp_f32_e32 v40, v40
	v_add_f32_e32 v39, 1.0, v39
	v_rcp_f32_e32 v39, v39
	v_add_f32_e32 v40, 1.0, v40
	v_rcp_f32_e32 v40, v40
	v_mul_f32_e32 v39, v39, v53
	v_mul_f32_e32 v40, v40, v49
	v_cvt_pk_bf16_f32 v39, v39, v40
	global_store_dwordx2 v[46:47], v[38:39], off offset:64
	s_waitcnt vmcnt(22)
	v_mov_b64_e32 v[38:39], v[160:161]
	ds_read_b128 v[40:43], v172 offset:192
	v_lshlrev_b32_e32 v44, 16, v38
	s_waitcnt lgkmcnt(0)
	v_add_f32_e32 v34, v34, v40
	v_add_f32_e32 v35, v35, v41
	v_mul_f32_e32 v34, 0xbfb8aa3b, v34
	v_mul_f32_e32 v35, 0xbfb8aa3b, v35
	v_exp_f32_e32 v34, v34
	v_exp_f32_e32 v35, v35
	v_and_b32_e32 v38, 0xffff0000, v38
	v_lshlrev_b32_e32 v45, 16, v39
	v_add_f32_e32 v34, 1.0, v34
	v_add_f32_e32 v35, 1.0, v35
	v_rcp_f32_e32 v34, v34
	v_rcp_f32_e32 v35, v35
	v_and_b32_e32 v39, 0xffff0000, v39
	v_mul_f32_e32 v34, v34, v44
	v_mul_f32_e32 v35, v35, v38
	v_cvt_pk_bf16_f32 v34, v34, v35
	v_add_f32_e32 v35, v36, v42
	v_mul_f32_e32 v35, 0xbfb8aa3b, v35
	v_add_f32_e32 v36, v37, v43
	v_exp_f32_e32 v35, v35
	v_mul_f32_e32 v36, 0xbfb8aa3b, v36
	v_exp_f32_e32 v36, v36
	v_add_f32_e32 v35, 1.0, v35
	v_rcp_f32_e32 v35, v35
	v_add_f32_e32 v36, 1.0, v36
	v_rcp_f32_e32 v36, v36
	v_mul_f32_e32 v35, v35, v45
	v_mul_f32_e32 v36, v36, v39
	v_cvt_pk_bf16_f32 v35, v35, v36
	global_store_dwordx2 v[46:47], v[34:35], off offset:96
	v_lshl_add_u64 v[34:35], s[24:25], 0, v[208:209]
	v_lshl_add_u64 v[34:35], v[34:35], 0, v[0:1]
	s_waitcnt vmcnt(21)
	v_mov_b64_e32 v[40:41], v[162:163]
	ds_read_b128 v[36:39], v172
	v_lshlrev_b32_e32 v42, 16, v40
	s_waitcnt lgkmcnt(0)
	v_add_f32_e32 v30, v30, v36
	v_add_f32_e32 v31, v31, v37
	v_mul_f32_e32 v30, 0xbfb8aa3b, v30
	v_mul_f32_e32 v31, 0xbfb8aa3b, v31
	v_exp_f32_e32 v30, v30
	v_exp_f32_e32 v31, v31
	v_and_b32_e32 v40, 0xffff0000, v40
	v_lshlrev_b32_e32 v43, 16, v41
	v_add_f32_e32 v30, 1.0, v30
	v_add_f32_e32 v31, 1.0, v31
	v_rcp_f32_e32 v30, v30
	v_rcp_f32_e32 v31, v31
	v_and_b32_e32 v41, 0xffff0000, v41
	v_mul_f32_e32 v30, v30, v42
	v_mul_f32_e32 v31, v31, v40
	v_cvt_pk_bf16_f32 v36, v30, v31
	v_add_f32_e32 v30, v32, v38
	v_add_f32_e32 v31, v33, v39
	v_mul_f32_e32 v30, 0xbfb8aa3b, v30
	v_mul_f32_e32 v31, 0xbfb8aa3b, v31
	v_exp_f32_e32 v30, v30
	v_exp_f32_e32 v31, v31
	v_add_f32_e32 v30, 1.0, v30
	v_add_f32_e32 v31, 1.0, v31
	v_rcp_f32_e32 v30, v30
	v_rcp_f32_e32 v31, v31
	v_mul_f32_e32 v30, v30, v43
	v_mul_f32_e32 v31, v31, v41
	v_cvt_pk_bf16_f32 v37, v30, v31
	v_lshl_add_u64 v[30:31], s[22:23], 0, v[208:209]
	v_lshl_add_u64 v[30:31], v[30:31], 0, v[0:1]
	global_store_dwordx2 v[30:31], v[36:37], off
	s_waitcnt vmcnt(20)
	v_mov_b64_e32 v[32:33], v[164:165]
	ds_read_b128 v[36:39], v172 offset:64
	v_lshlrev_b32_e32 v40, 16, v32
	s_waitcnt lgkmcnt(0)
	v_add_f32_e32 v26, v26, v36
	v_add_f32_e32 v27, v27, v37
	v_mul_f32_e32 v26, 0xbfb8aa3b, v26
	v_mul_f32_e32 v27, 0xbfb8aa3b, v27
	v_exp_f32_e32 v26, v26
	v_exp_f32_e32 v27, v27
	v_and_b32_e32 v32, 0xffff0000, v32
	v_lshlrev_b32_e32 v41, 16, v33
	v_add_f32_e32 v26, 1.0, v26
	v_add_f32_e32 v27, 1.0, v27
	v_rcp_f32_e32 v26, v26
	v_rcp_f32_e32 v27, v27
	v_and_b32_e32 v33, 0xffff0000, v33
	v_mul_f32_e32 v26, v26, v40
	v_mul_f32_e32 v27, v27, v32
	v_cvt_pk_bf16_f32 v26, v26, v27
	v_add_f32_e32 v27, v28, v38
	v_mul_f32_e32 v27, 0xbfb8aa3b, v27
	v_add_f32_e32 v28, v29, v39
	v_exp_f32_e32 v27, v27
	v_mul_f32_e32 v28, 0xbfb8aa3b, v28
	v_exp_f32_e32 v28, v28
	v_add_f32_e32 v27, 1.0, v27
	v_rcp_f32_e32 v27, v27
	v_add_f32_e32 v28, 1.0, v28
	v_rcp_f32_e32 v28, v28
	v_mul_f32_e32 v27, v27, v41
	v_mul_f32_e32 v28, v28, v33
	v_cvt_pk_bf16_f32 v27, v27, v28
	global_store_dwordx2 v[30:31], v[26:27], off offset:32
	s_waitcnt vmcnt(19)
	v_mov_b64_e32 v[32:33], v[166:167]
	ds_read_b128 v[26:29], v172 offset:128
	v_lshlrev_b32_e32 v36, 16, v32
	s_waitcnt lgkmcnt(0)
	v_add_f32_e32 v22, v22, v26
	v_add_f32_e32 v23, v23, v27
	v_mul_f32_e32 v22, 0xbfb8aa3b, v22
	v_mul_f32_e32 v23, 0xbfb8aa3b, v23
	v_exp_f32_e32 v22, v22
	v_exp_f32_e32 v23, v23
	v_and_b32_e32 v32, 0xffff0000, v32
	v_lshlrev_b32_e32 v37, 16, v33
	v_add_f32_e32 v22, 1.0, v22
	v_add_f32_e32 v23, 1.0, v23
	v_rcp_f32_e32 v22, v22
	v_rcp_f32_e32 v23, v23
	v_and_b32_e32 v33, 0xffff0000, v33
	v_mul_f32_e32 v22, v22, v36
	v_mul_f32_e32 v23, v23, v32
	v_cvt_pk_bf16_f32 v22, v22, v23
	v_add_f32_e32 v23, v24, v28
	v_mul_f32_e32 v23, 0xbfb8aa3b, v23
	v_add_f32_e32 v24, v25, v29
	v_exp_f32_e32 v23, v23
	v_mul_f32_e32 v24, 0xbfb8aa3b, v24
	v_exp_f32_e32 v24, v24
	v_add_f32_e32 v23, 1.0, v23
	v_rcp_f32_e32 v23, v23
	v_add_f32_e32 v24, 1.0, v24
	v_rcp_f32_e32 v24, v24
	v_mul_f32_e32 v23, v23, v37
	v_mul_f32_e32 v24, v24, v33
	v_cvt_pk_bf16_f32 v23, v23, v24
	global_store_dwordx2 v[30:31], v[22:23], off offset:64
	s_waitcnt vmcnt(18)
	v_mov_b64_e32 v[22:23], v[168:169]
	ds_read_b128 v[24:27], v172 offset:192
	v_lshlrev_b32_e32 v28, 16, v22
	s_waitcnt lgkmcnt(0)
	v_add_f32_e32 v18, v18, v24
	v_add_f32_e32 v19, v19, v25
	v_mul_f32_e32 v18, 0xbfb8aa3b, v18
	v_mul_f32_e32 v19, 0xbfb8aa3b, v19
	v_exp_f32_e32 v18, v18
	v_exp_f32_e32 v19, v19
	v_and_b32_e32 v22, 0xffff0000, v22
	v_lshlrev_b32_e32 v29, 16, v23
	v_add_f32_e32 v18, 1.0, v18
	v_add_f32_e32 v19, 1.0, v19
	v_rcp_f32_e32 v18, v18
	v_rcp_f32_e32 v19, v19
	v_and_b32_e32 v23, 0xffff0000, v23
	v_mul_f32_e32 v18, v18, v28
	v_mul_f32_e32 v19, v19, v22
	v_cvt_pk_bf16_f32 v18, v18, v19
	v_add_f32_e32 v19, v20, v26
	v_mul_f32_e32 v19, 0xbfb8aa3b, v19
	v_add_f32_e32 v20, v21, v27
	v_exp_f32_e32 v19, v19
	v_mul_f32_e32 v20, 0xbfb8aa3b, v20
	v_exp_f32_e32 v20, v20
	v_add_f32_e32 v19, 1.0, v19
	v_rcp_f32_e32 v19, v19
	v_add_f32_e32 v20, 1.0, v20
	v_rcp_f32_e32 v20, v20
	v_mul_f32_e32 v19, v19, v29
	v_mul_f32_e32 v20, v20, v23
	v_cvt_pk_bf16_f32 v19, v19, v20
	global_store_dwordx2 v[30:31], v[18:19], off offset:96
	v_lshl_add_u64 v[18:19], s[24:25], 0, v[210:211]
	v_lshl_add_u64 v[18:19], v[18:19], 0, v[0:1]
	s_waitcnt vmcnt(17)
	v_mov_b64_e32 v[24:25], v[142:143]
	ds_read_b128 v[20:23], v172
	v_lshlrev_b32_e32 v26, 16, v24
	s_waitcnt lgkmcnt(0)
	v_add_f32_e32 v14, v14, v20
	v_add_f32_e32 v15, v15, v21
	v_mul_f32_e32 v14, 0xbfb8aa3b, v14
	v_mul_f32_e32 v15, 0xbfb8aa3b, v15
	v_exp_f32_e32 v14, v14
	v_exp_f32_e32 v15, v15
	v_and_b32_e32 v24, 0xffff0000, v24
	v_lshlrev_b32_e32 v27, 16, v25
	v_add_f32_e32 v14, 1.0, v14
	v_add_f32_e32 v15, 1.0, v15
	v_rcp_f32_e32 v14, v14
	v_rcp_f32_e32 v15, v15
	v_and_b32_e32 v25, 0xffff0000, v25
	v_mul_f32_e32 v14, v14, v26
	v_mul_f32_e32 v15, v15, v24
	v_cvt_pk_bf16_f32 v20, v14, v15
	v_add_f32_e32 v14, v16, v22
	v_add_f32_e32 v15, v17, v23
	v_mul_f32_e32 v14, 0xbfb8aa3b, v14
	v_mul_f32_e32 v15, 0xbfb8aa3b, v15
	v_exp_f32_e32 v14, v14
	v_exp_f32_e32 v15, v15
	v_add_f32_e32 v14, 1.0, v14
	v_add_f32_e32 v15, 1.0, v15
	v_rcp_f32_e32 v14, v14
	v_rcp_f32_e32 v15, v15
	v_mul_f32_e32 v14, v14, v27
	v_mul_f32_e32 v15, v15, v25
	v_cvt_pk_bf16_f32 v21, v14, v15
	v_lshl_add_u64 v[14:15], s[22:23], 0, v[210:211]
	v_lshl_add_u64 v[14:15], v[14:15], 0, v[0:1]
	global_store_dwordx2 v[14:15], v[20:21], off
	s_waitcnt vmcnt(16)
	v_mov_b64_e32 v[16:17], v[144:145]
	ds_read_b128 v[20:23], v172 offset:64
	v_lshlrev_b32_e32 v0, 16, v16
	s_waitcnt lgkmcnt(0)
	v_add_f32_e32 v10, v10, v20
	v_mul_f32_e32 v10, 0xbfb8aa3b, v10
	v_exp_f32_e32 v10, v10
	v_and_b32_e32 v16, 0xffff0000, v16
	v_lshlrev_b32_e32 v24, 16, v17
	v_and_b32_e32 v17, 0xffff0000, v17
	v_add_f32_e32 v10, 1.0, v10
	v_rcp_f32_e32 v10, v10
	s_nop 0
	v_mul_f32_e32 v0, v10, v0
	v_add_f32_e32 v10, v11, v21
	v_mul_f32_e32 v10, 0xbfb8aa3b, v10
	v_exp_f32_e32 v10, v10
	v_add_f32_e32 v11, v13, v23
	v_mul_f32_e32 v11, 0xbfb8aa3b, v11
	v_exp_f32_e32 v11, v11
	v_add_f32_e32 v10, 1.0, v10
	v_rcp_f32_e32 v10, v10
	v_add_f32_e32 v11, 1.0, v11
	v_rcp_f32_e32 v11, v11
	v_mul_f32_e32 v10, v10, v16
	v_cvt_pk_bf16_f32 v10, v0, v10
	v_add_f32_e32 v0, v12, v22
	v_mul_f32_e32 v0, 0xbfb8aa3b, v0
	v_exp_f32_e32 v0, v0
	v_mul_f32_e32 v11, v11, v17
	v_add_f32_e32 v0, 1.0, v0
	v_rcp_f32_e32 v0, v0
	s_nop 0
	v_mul_f32_e32 v0, v0, v24
	v_cvt_pk_bf16_f32 v11, v0, v11
	global_store_dwordx2 v[14:15], v[10:11], off offset:32
	s_waitcnt vmcnt(15)
	v_mov_b64_e32 v[16:17], v[146:147]
	ds_read_b128 v[10:13], v172 offset:128
	v_lshlrev_b32_e32 v0, 16, v16
	s_waitcnt lgkmcnt(0)
	v_add_f32_e32 v6, v6, v10
	v_mul_f32_e32 v6, 0xbfb8aa3b, v6
	v_exp_f32_e32 v6, v6
	v_and_b32_e32 v16, 0xffff0000, v16
	v_lshlrev_b32_e32 v20, 16, v17
	v_and_b32_e32 v17, 0xffff0000, v17
	v_add_f32_e32 v6, 1.0, v6
	v_rcp_f32_e32 v6, v6
	s_nop 0
	v_mul_f32_e32 v0, v6, v0
	v_add_f32_e32 v6, v7, v11
	v_mul_f32_e32 v6, 0xbfb8aa3b, v6
	v_exp_f32_e32 v6, v6
	v_add_f32_e32 v7, v9, v13
	v_mul_f32_e32 v7, 0xbfb8aa3b, v7
	v_exp_f32_e32 v7, v7
	v_add_f32_e32 v6, 1.0, v6
	v_rcp_f32_e32 v6, v6
	v_add_f32_e32 v7, 1.0, v7
	v_rcp_f32_e32 v7, v7
	v_mul_f32_e32 v6, v6, v16
	v_cvt_pk_bf16_f32 v6, v0, v6
	v_add_f32_e32 v0, v8, v12
	v_mul_f32_e32 v0, 0xbfb8aa3b, v0
	v_exp_f32_e32 v0, v0
	v_mul_f32_e32 v7, v7, v17
	v_add_f32_e32 v0, 1.0, v0
	v_rcp_f32_e32 v0, v0
	s_nop 0
	v_mul_f32_e32 v0, v0, v20
	v_cvt_pk_bf16_f32 v7, v0, v7
	global_store_dwordx2 v[14:15], v[6:7], off offset:64
	s_waitcnt vmcnt(14)
	v_mov_b64_e32 v[6:7], v[148:149]
	ds_read_b128 v[8:11], v172 offset:192
	v_lshlrev_b32_e32 v0, 16, v6
	s_waitcnt lgkmcnt(0)
	v_add_f32_e32 v2, v2, v8
	v_mul_f32_e32 v2, 0xbfb8aa3b, v2
	v_exp_f32_e32 v2, v2
	v_and_b32_e32 v6, 0xffff0000, v6
	v_lshlrev_b32_e32 v12, 16, v7
	v_and_b32_e32 v7, 0xffff0000, v7
	v_add_f32_e32 v2, 1.0, v2
	v_rcp_f32_e32 v2, v2
	s_nop 0
	v_mul_f32_e32 v0, v2, v0
	v_add_f32_e32 v2, v3, v9
	v_mul_f32_e32 v2, 0xbfb8aa3b, v2
	v_exp_f32_e32 v2, v2
	v_add_f32_e32 v3, v5, v11
	v_mul_f32_e32 v3, 0xbfb8aa3b, v3
	v_exp_f32_e32 v3, v3
	v_add_f32_e32 v2, 1.0, v2
	v_rcp_f32_e32 v2, v2
	v_add_f32_e32 v3, 1.0, v3
	v_rcp_f32_e32 v3, v3
	v_mul_f32_e32 v2, v2, v6
	v_cvt_pk_bf16_f32 v2, v0, v2
	v_add_f32_e32 v0, v4, v10
	v_mul_f32_e32 v0, 0xbfb8aa3b, v0
	v_exp_f32_e32 v0, v0
	v_mul_f32_e32 v3, v3, v7
	v_add_f32_e32 v0, 1.0, v0
	v_rcp_f32_e32 v0, v0
	s_nop 0
	v_mul_f32_e32 v0, v0, v12
	v_cvt_pk_bf16_f32 v3, v0, v3
	global_store_dwordx2 v[14:15], v[2:3], off offset:96
	s_andn2_b64 vcc, exec, s[18:19]
	s_mov_b64 s[18:19], -1
	s_cbranch_vccnz .LBB0_1384
	s_mov_b64 s[18:19], 0
	s_branch .LBB0_1384
